# grid barrier: drop the now-unread per-XCD generation bump and the wait before the leader's acquire invalidate
# baseline (speedup 1.0000x reference)
.LBB0_1213:
	s_or_b64 exec, exec, s[2:3]
	s_mov_b64 s[2:3], exec
	v_mbcnt_lo_u32_b32 v0, s2, 0
	v_mbcnt_hi_u32_b32 v0, s3, v0
	v_cmp_eq_u32_e32 vcc, 0, v0
	s_nop 0
	buffer_inv sc1
	s_and_saveexec_b64 s[4:5], vcc
	s_cbranch_execz .LBB0_1215
	s_bcnt1_i32_b64 s2, s[2:3]
	v_mov_b32_e32 v0, s2
	v_readlane_b32 s2, v252, 9
	v_readlane_b32 s3, v252, 10
	s_nop 4
	s_nop 0
